# softmax row-max chain trimmed: dropped redundant canonicalising max ops, rescale factor (sub/mul/exp) only computed on the rare rescale path via out-of-line block
# speedup vs baseline: 1.0076x; 1.0017x over previous
; #define SBAR() __builtin_amdgcn_sched_barrier(0)
; #define SLOAD(i, k0) do { sr_[i].vs0 = *reinterpret_cast<const bf16x8*>(vptr + (size_t)((k0) + sr) * vstr); \
;     sr_[i].vs1 = *reinterpret_cast<const bf16x8*>(vptr + (size_t)((k0) + 32 + sr) * vstr); \
;     sr_[i].ks0 = *reinterpret_cast<const bf16x8*>(kptr + (size_t)((k0) + sr) * kstr); \
;     sr_[i].ks1 = *reinterpret_cast<const bf16x8*>(kptr + (size_t)((k0) + 32 + sr) * kstr); } while (0)
; __device__ __forceinline__ void partialSM(f32x16& p0, f32x16& p1, float& m_reg, float& mn, float& alpha, float C, float thr) {
;   float pmax = p0[0];
; #pragma unroll
;   for (int r = 1; r < 16; ++r) pmax = fmaxf(pmax, p0[r]);
; #pragma unroll
;   for (int r = 0; r < 16; ++r) pmax = fmaxf(pmax, p1[r]);
;   { auto rr = __builtin_amdgcn_permlane32_swap(__float_as_uint(pmax), __float_as_uint(pmax), false, false);
;     pmax = fmaxf(__uint_as_float(rr[0]), __uint_as_float(rr[1])); }
;   if (__builtin_expect(__all(pmax - m_reg <= thr), 1)) { mn = m_reg; alpha = 1.f; }
;   else { mn = fmaxf(m_reg, pmax); alpha = __builtin_amdgcn_exp2f((m_reg - mn) * C); m_reg = mn; }
;   const float mnC = -mn * C;
; #pragma unroll
;   for (int r = 0; r < 16; ++r) p0[r] = fmaf(p0[r], C, mnC);
; #pragma unroll
;   for (int r = 0; r < 16; ++r) p1[r] = fmaf(p1[r], C, mnC);
; #pragma unroll
;   for (int r = 0; r < 16; ++r) p0[r] = __builtin_amdgcn_exp2f(p0[r]);
; }
; __device__ __forceinline__ void finishSM(f32x16& p0, f32x16& p1, float alpha, float& l_reg, bf16x8& pa0, bf16x8& pa1, bf16x8& pa2, bf16x8& pa3) {
; #pragma unroll
;   for (int r = 0; r < 16; ++r) p1[r] = __builtin_amdgcn_exp2f(p1[r]);
;   float ps = 0;
; #pragma unroll
;   for (int r = 0; r < 16; ++r) ps += p0[r];
; #pragma unroll
;   for (int r = 0; r < 16; ++r) ps += p1[r];
;   { auto rr = __builtin_amdgcn_permlane32_swap(__float_as_uint(ps), __float_as_uint(ps), false, false);
;     ps = __uint_as_float(rr[0]) + __uint_as_float(rr[1]); }
;   l_reg = l_reg * alpha + ps;
;     ...
;   PK4(p0, 0, pa0); PK4(p0, 8, pa1); PK4(p1, 0, pa2); PK4(p1, 8, pa3);
;     ...
; }
; template <int NDQ, int NDV> ...
;     ...
;     SBAR(); qkt<NDQ>(pB0, pB1, K_lds + SHM_K, qr, r32, hi);
;     finishSM(pA0, pA1, alA, l_reg, pa0, pa1, pa2, pa3); SBAR();
;     SLOAD(SO, (j + 2) * 64); SBAR();
;     pv_d0<NDV>(o, vb0, pa0, pa1, pa2, pa3); partialSM(pB0, pB1, m_reg, mnB, alB, Cs, thr);
.LBB0_1488:
	ds_read_b128 v[32:35], v175 offset:49152
	ds_read_b128 v[36:39], v175 offset:57344
	ds_read_b128 v[192:195], v176 offset:49152
	ds_read_b128 v[196:199], v176 offset:57344
	ds_read_b128 v[200:203], v177 offset:49152
	ds_read_b128 v[204:207], v177 offset:57344
	ds_read_b128 v[208:211], v178 offset:49152
	ds_read_b128 v[212:215], v178 offset:57344
	ds_read_b128 v[216:219], v179 offset:49152
	ds_read_b128 v[220:223], v179 offset:57344
	v_add_f32_e32 v121, 0, v130
	v_add_f32_e32 v121, v134, v121
	s_waitcnt lgkmcnt(9)
	v_mfma_f32_32x32x16_bf16 v[48:63], v[32:35], v[84:87], 0
	v_add_f32_e32 v121, v131, v121
	v_add_f32_e32 v121, v135, v121
	v_add_f32_e32 v121, v132, v121
	v_add_f32_e32 v121, v185, v121
	v_add_f32_e32 v121, v133, v121
	v_add_f32_e32 v121, v186, v121
	v_add_f32_e32 v121, v122, v121
	v_add_f32_e32 v121, v125, v121
	s_waitcnt lgkmcnt(8)
	v_mfma_f32_32x32x16_bf16 v[32:47], v[36:39], v[84:87], 0
	v_add_f32_e32 v121, v123, v121
	v_add_f32_e32 v121, v126, v121
	v_exp_f32_e32 v116, v116
	v_add_f32_e32 v121, v124, v121
	v_exp_f32_e32 v117, v117
	v_add_f32_e32 v121, v127, v121
	s_waitcnt lgkmcnt(7)
	v_mfma_f32_32x32x16_bf16 v[48:63], v[192:195], v[80:83], v[48:63]
	v_exp_f32_e32 v114, v114
	v_add_f32_e32 v121, v128, v121
	v_exp_f32_e32 v115, v115
	v_add_f32_e32 v121, v129, v121
	v_exp_f32_e32 v110, v110
	s_waitcnt lgkmcnt(6)
	v_mfma_f32_32x32x16_bf16 v[32:47], v[196:199], v[80:83], v[32:47]
	v_add_f32_e32 v121, v116, v121
	v_exp_f32_e32 v111, v111
	v_add_f32_e32 v121, v117, v121
	v_exp_f32_e32 v106, v106
	v_add_f32_e32 v121, v114, v121
	s_waitcnt lgkmcnt(5)
	v_mfma_f32_32x32x16_bf16 v[48:63], v[200:203], v[76:79], v[48:63]
	ds_read_b128 v[224:227], v180 offset:49152
	ds_read_b128 v[228:231], v180 offset:57344
	v_exp_f32_e32 v107, v107
	v_add_f32_e32 v121, v115, v121
	v_exp_f32_e32 v104, v104
	v_add_f32_e32 v121, v110, v121
	v_exp_f32_e32 v105, v105
	s_waitcnt lgkmcnt(6)
	v_mfma_f32_32x32x16_bf16 v[32:47], v[204:207], v[76:79], v[32:47]
	v_add_f32_e32 v121, v111, v121
	v_exp_f32_e32 v118, v118
	v_add_f32_e32 v121, v106, v121
	v_exp_f32_e32 v119, v119
	v_add_f32_e32 v121, v107, v121
	s_waitcnt lgkmcnt(5)
	v_mfma_f32_32x32x16_bf16 v[48:63], v[208:211], v[72:75], v[48:63]
	v_exp_f32_e32 v112, v112
	v_add_f32_e32 v121, v104, v121
	v_exp_f32_e32 v113, v113
	v_add_f32_e32 v121, v105, v121
	v_exp_f32_e32 v108, v108
	s_waitcnt lgkmcnt(4)
	v_mfma_f32_32x32x16_bf16 v[32:47], v[212:215], v[72:75], v[32:47]
	v_add_f32_e32 v121, v118, v121
	v_exp_f32_e32 v109, v109
	v_add_f32_e32 v121, v119, v121
	v_add_f32_e32 v121, v112, v121
	v_add_f32_e32 v121, v113, v121
	v_add_f32_e32 v121, v108, v121
	v_add_f32_e32 v182, v109, v121
	s_waitcnt lgkmcnt(3)
	v_mfma_f32_32x32x16_bf16 v[48:63], v[216:219], v[68:71], v[48:63]
	v_mov_b32_e32 v183, v182
	v_cvt_pk_bf16_f32 v130, v130, v134
	v_cvt_pk_bf16_f32 v131, v131, v135
	v_cvt_pk_bf16_f32 v132, v132, v185
	v_cvt_pk_bf16_f32 v133, v133, v186
	v_cvt_pk_bf16_f32 v122, v122, v125
	v_cvt_pk_bf16_f32 v123, v123, v126
	v_cvt_pk_bf16_f32 v124, v124, v127
	s_waitcnt lgkmcnt(2)
	v_mfma_f32_32x32x16_bf16 v[32:47], v[220:223], v[68:71], v[32:47]
	v_cvt_pk_bf16_f32 v125, v128, v129
	v_cvt_pk_bf16_f32 v126, v116, v117
	v_cvt_pk_bf16_f32 v127, v114, v115
	v_cvt_pk_bf16_f32 v128, v110, v111
	v_cvt_pk_bf16_f32 v129, v106, v107
	v_cvt_pk_bf16_f32 v184, v104, v105
	v_cvt_pk_bf16_f32 v185, v118, v119
	v_cvt_pk_bf16_f32 v186, v112, v113
	s_waitcnt lgkmcnt(1)
	v_mfma_f32_32x32x16_bf16 v[48:63], v[224:227], v[64:67], v[48:63]
	v_permlane32_swap_b32_e32 v182, v183
	v_cvt_pk_bf16_f32 v187, v108, v109
	v_permlane32_swap_b32_e32 v184, v186
	v_permlane32_swap_b32_e32 v130, v132
	v_permlane32_swap_b32_e32 v131, v133
	v_permlane32_swap_b32_e32 v122, v124
	v_permlane32_swap_b32_e32 v123, v125
	v_permlane32_swap_b32_e32 v126, v128
	s_waitcnt lgkmcnt(0)
	v_mfma_f32_32x32x16_bf16 v[32:47], v[228:231], v[64:67], v[32:47]
	v_permlane32_swap_b32_e32 v127, v129
	v_permlane32_swap_b32_e32 v185, v187
	v_add_co_u32_e32 v104, vcc, s48, v154
	v_lshl_add_u64 v[112:113], v[150:151], 0, v[160:161]
	s_nop 0
	v_addc_co_u32_e32 v105, vcc, -1, v155, vcc
	v_add_co_u32_e32 v108, vcc, s49, v154
	v_lshl_add_u64 v[116:117], v[150:151], 0, v[158:159]
	s_nop 0
	v_addc_co_u32_e32 v109, vcc, -1, v155, vcc
	global_load_dwordx4 v[104:107], v[104:105], off
	s_nop 0
	global_load_dwordx4 v[108:111], v[108:109], off
	s_nop 0
	global_load_dwordx4 v[112:115], v[112:113], off
	s_nop 0
	global_load_dwordx4 v[116:119], v[116:117], off
	s_waitcnt vmcnt(4)
	ds_write_b128 v171, v[88:91] offset:32768
	ds_write_b128 v172, v[92:95] offset:32768
	ds_read_b64_tr_b16 v[192:193], v170 offset:0
	ds_read_b64_tr_b16 v[194:195], v170 offset:0x800
	ds_read_b64_tr_b16 v[196:197], v170 offset:0x1000
	ds_read_b64_tr_b16 v[198:199], v170 offset:0x1800
	ds_read_b64_tr_b16 v[200:201], v170 offset:0x2000
	ds_read_b64_tr_b16 v[202:203], v170 offset:0x2800
	ds_read_b64_tr_b16 v[204:205], v170 offset:0x3000
	ds_read_b64_tr_b16 v[206:207], v170 offset:0x3800
	s_waitcnt lgkmcnt(6)
	v_mfma_f32_32x32x16_bf16 v[0:15], v[130:133], v[192:195], v[0:15]
	ds_read_b64_tr_b16 v[192:193], v170 offset:0x200
	ds_read_b64_tr_b16 v[194:195], v170 offset:0xa00
	v_max_f32_e32 v121, v48, v49
	v_max3_f32 v121, v121, v50, v51
	v_max3_f32 v121, v121, v52, v53
	v_max3_f32 v121, v121, v54, v55
	v_max3_f32 v121, v121, v56, v57
	v_max3_f32 v121, v121, v58, v59
	v_max3_f32 v121, v121, v60, v61
	v_max3_f32 v121, v121, v62, v63
	v_max3_f32 v121, v121, v32, v33
	v_max3_f32 v121, v121, v34, v35
	v_max3_f32 v121, v121, v36, v37
	v_max3_f32 v121, v121, v38, v39
	s_waitcnt lgkmcnt(6)
	v_mfma_f32_32x32x16_bf16 v[0:15], v[122:125], v[196:199], v[0:15]
	ds_read_b64_tr_b16 v[196:197], v170 offset:0x1200
	ds_read_b64_tr_b16 v[198:199], v170 offset:0x1a00
	v_max3_f32 v121, v121, v40, v41
	v_max3_f32 v121, v121, v42, v43
	v_max3_f32 v121, v121, v44, v45
	v_max3_f32 v121, v121, v46, v47
	v_mov_b32_e32 v134, v121
	s_nop 1
	v_permlane32_swap_b32_e32 v121, v134
	v_max_f32_e32 v121, v121, v134
	v_sub_f32_e32 v135, v121, v120
	v_max_f32_e32 v121, v120, v121
	v_cmp_ge_f32_e32 vcc, s46, v135
	s_cmp_eq_u64 vcc, exec
	s_waitcnt lgkmcnt(6)
	v_mfma_f32_32x32x16_bf16 v[0:15], v[126:129], v[200:203], v[0:15]
	ds_read_b64_tr_b16 v[200:201], v170 offset:0x2200
	ds_read_b64_tr_b16 v[202:203], v170 offset:0x2a00
	ds_read_b64_tr_b16 v[208:209], v170 offset:0x3200
	ds_read_b64_tr_b16 v[210:211], v170 offset:0x3a00
	s_cselect_b64 s[6:7], -1, 0
	s_cbranch_scc0 .Lmla_rareA
; __device__ __forceinline__ void partialSM(f32x16& p0, f32x16& p1, float& m_reg, float& mn, float& alpha, float C, float thr) {
;     ...
;   if (__builtin_expect(__all(pmax - m_reg <= thr), 1)) { mn = m_reg; alpha = 1.f; }
;   else { mn = fmaxf(m_reg, pmax); alpha = __builtin_amdgcn_exp2f((m_reg - mn) * C); m_reg = mn; }
;   const float mnC = -mn * C;
; #pragma unroll
;   for (int r = 0; r < 16; ++r) p0[r] = fmaf(p0[r], C, mnC);
; #pragma unroll
;   for (int r = 0; r < 16; ++r) p1[r] = fmaf(p1[r], C, mnC);
; #pragma unroll
;   for (int r = 0; r < 16; ++r) p0[r] = __builtin_amdgcn_exp2f(p0[r]);
.Lmla_backA:
	v_cndmask_b32_e64 v253, v121, v120, s[6:7]
	v_mul_f32_e32 v251, 0xbe16c740, v253
	s_waitcnt lgkmcnt(8)
	v_mfma_f32_32x32x16_bf16 v[0:15], v[184:187], v[204:207], v[0:15]
	v_fmamk_f32 v48, v48, 0x3e16c740, v251
	v_fmamk_f32 v49, v49, 0x3e16c740, v251
	v_fmamk_f32 v50, v50, 0x3e16c740, v251
	v_fmamk_f32 v51, v51, 0x3e16c740, v251
	v_fmamk_f32 v52, v52, 0x3e16c740, v251
	v_fmamk_f32 v53, v53, 0x3e16c740, v251
	v_fmamk_f32 v54, v54, 0x3e16c740, v251
	v_fmamk_f32 v55, v55, 0x3e16c740, v251
	v_fmamk_f32 v56, v56, 0x3e16c740, v251
	v_fmamk_f32 v57, v57, 0x3e16c740, v251
	v_fmamk_f32 v58, v58, 0x3e16c740, v251
	v_fmamk_f32 v59, v59, 0x3e16c740, v251
	s_waitcnt lgkmcnt(6)
	v_mfma_f32_32x32x16_bf16 v[16:31], v[130:133], v[192:195], v[16:31]
	v_fmamk_f32 v60, v60, 0x3e16c740, v251
	v_fmamk_f32 v61, v61, 0x3e16c740, v251
	v_fmamk_f32 v62, v62, 0x3e16c740, v251
	v_fmamk_f32 v63, v63, 0x3e16c740, v251
	v_exp_f32_e32 v120, v48
	v_exp_f32_e32 v135, v49
	v_exp_f32_e32 v121, v50
	v_exp_f32_e32 v134, v51
	v_exp_f32_e32 v133, v53
	v_exp_f32_e32 v132, v55
	s_waitcnt lgkmcnt(4)
	v_mfma_f32_32x32x16_bf16 v[16:31], v[122:125], v[196:199], v[16:31]
	v_exp_f32_e32 v131, v57
	v_exp_f32_e32 v130, v59
	v_exp_f32_e32 v122, v52
	v_exp_f32_e32 v123, v54
	v_exp_f32_e32 v124, v56
	v_exp_f32_e32 v125, v58
	s_waitcnt lgkmcnt(2)
	v_mfma_f32_32x32x16_bf16 v[16:31], v[126:129], v[200:203], v[16:31]
	v_exp_f32_e32 v126, v60
	v_exp_f32_e32 v129, v61
	v_exp_f32_e32 v127, v62
	v_exp_f32_e32 v128, v63
	s_waitcnt lgkmcnt(0)
	v_mfma_f32_32x32x16_bf16 v[16:31], v[184:187], v[208:211], v[16:31]
	s_barrier
	s_waitcnt vmcnt(4)
	v_cndmask_b32_e64 v184, v252, 1.0, s[6:7]
	v_cmp_gt_f32_e32 vcc, 1.0, v184
	s_waitcnt vmcnt(4)
	ds_write_b128 v173, v[96:99]
	ds_write_b128 v174, v[100:103]
	s_cbranch_vccz .LBB0_1492
	s_and_saveexec_b64 s[10:11], s[4:5]
	ds_write_b32 v167, v184 offset:128
	s_or_b64 exec, exec, s[10:11]
	s_waitcnt lgkmcnt(0)
	v_add_u32_e32 v208, v149, v146
	ds_read_b128 v[192:195], v208 offset:224
	ds_read_b128 v[196:199], v208 offset:192
	ds_read_b128 v[200:203], v208 offset:160
	ds_read_b128 v[204:207], v208 offset:128
	s_waitcnt lgkmcnt(3)
	v_pk_mul_f32 v[12:13], v[12:13], v[192:193]
	s_waitcnt lgkmcnt(2)
	v_pk_mul_f32 v[8:9], v[8:9], v[196:197]
	s_waitcnt lgkmcnt(1)
	v_pk_mul_f32 v[4:5], v[4:5], v[200:201]
	v_pk_mul_f32 v[14:15], v[14:15], v[194:195]
	v_pk_mul_f32 v[10:11], v[10:11], v[198:199]
	v_pk_mul_f32 v[6:7], v[6:7], v[202:203]
	s_waitcnt lgkmcnt(0)
	v_pk_mul_f32 v[2:3], v[2:3], v[206:207]
	v_pk_mul_f32 v[0:1], v[0:1], v[204:205]
	v_pk_mul_f32 v[28:29], v[28:29], v[192:193]
	v_pk_mul_f32 v[24:25], v[24:25], v[196:197]
	v_pk_mul_f32 v[20:21], v[20:21], v[200:201]
	v_pk_mul_f32 v[30:31], v[30:31], v[194:195]
	v_pk_mul_f32 v[26:27], v[26:27], v[198:199]
	v_pk_mul_f32 v[22:23], v[22:23], v[202:203]
	v_pk_mul_f32 v[18:19], v[18:19], v[206:207]
	v_pk_mul_f32 v[16:17], v[16:17], v[204:205]

; #define SBAR() __builtin_amdgcn_sched_barrier(0)
; #define SLOAD(i, k0) do { sr_[i].vs0 = *reinterpret_cast<const bf16x8*>(vptr + (size_t)((k0) + sr) * vstr); \
;     sr_[i].vs1 = *reinterpret_cast<const bf16x8*>(vptr + (size_t)((k0) + 32 + sr) * vstr); \
;     sr_[i].ks0 = *reinterpret_cast<const bf16x8*>(kptr + (size_t)((k0) + sr) * kstr); \
;     sr_[i].ks1 = *reinterpret_cast<const bf16x8*>(kptr + (size_t)((k0) + 32 + sr) * kstr); } while (0)
; __device__ __forceinline__ void partialSM(f32x16& p0, f32x16& p1, float& m_reg, float& mn, float& alpha, float C, float thr) {
;   float pmax = p0[0];
; #pragma unroll
;   for (int r = 1; r < 16; ++r) pmax = fmaxf(pmax, p0[r]);
; #pragma unroll
;   for (int r = 0; r < 16; ++r) pmax = fmaxf(pmax, p1[r]);
;   { auto rr = __builtin_amdgcn_permlane32_swap(__float_as_uint(pmax), __float_as_uint(pmax), false, false);
;     pmax = fmaxf(__uint_as_float(rr[0]), __uint_as_float(rr[1])); }
;   if (__builtin_expect(__all(pmax - m_reg <= thr), 1)) { mn = m_reg; alpha = 1.f; }
;   else { mn = fmaxf(m_reg, pmax); alpha = __builtin_amdgcn_exp2f((m_reg - mn) * C); m_reg = mn; }
;   const float mnC = -mn * C;
; #pragma unroll
;   for (int r = 0; r < 16; ++r) p0[r] = fmaf(p0[r], C, mnC);
; #pragma unroll
;   for (int r = 0; r < 16; ++r) p1[r] = fmaf(p1[r], C, mnC);
; #pragma unroll
;   for (int r = 0; r < 16; ++r) p0[r] = __builtin_amdgcn_exp2f(p0[r]);
; }
; template <int NDQ, int NDV> ...
;     ...
;     SBAR(); qkt<NDQ>(pA0, pA1, K_lds, qr, r32, hi);
;     finishSM(pB0, pB1, alB, l_reg, pa0, pa1, pa2, pa3); SBAR();
;     if (j + 3 < NT) SLOAD(SE, (j + 3) * 64); SBAR();
;     pv_d0<NDV>(o, vb0 + SHM_V, pa0, pa1, pa2, pa3); partialSM(pA0, pA1, m_reg, mnA, alA, Cs, thr);
.Lmla_nodrain2:
	ds_write_b128 v171, v[112:115] offset:49152
	ds_write_b128 v172, v[116:119] offset:49152
	ds_read_b64_tr_b16 v[192:193], v168 offset:0
	ds_read_b64_tr_b16 v[194:195], v168 offset:0x800
	ds_read_b64_tr_b16 v[196:197], v168 offset:0x1000
	ds_read_b64_tr_b16 v[198:199], v168 offset:0x1800
	ds_read_b64_tr_b16 v[200:201], v168 offset:0x2000
	ds_read_b64_tr_b16 v[202:203], v168 offset:0x2800
	ds_read_b64_tr_b16 v[204:205], v168 offset:0x3000
	ds_read_b64_tr_b16 v[206:207], v168 offset:0x3800
	s_waitcnt lgkmcnt(6)
	v_mfma_f32_32x32x16_bf16 v[0:15], v[120:123], v[192:195], v[0:15]
	ds_read_b64_tr_b16 v[192:193], v168 offset:0x200
	ds_read_b64_tr_b16 v[194:195], v168 offset:0xa00
	v_max_f32_e32 v186, v48, v49
	v_max3_f32 v186, v186, v50, v51
	v_max3_f32 v186, v186, v52, v53
	v_max3_f32 v186, v186, v54, v55
	v_max3_f32 v186, v186, v56, v57
	v_max3_f32 v186, v186, v58, v59
	v_max3_f32 v186, v186, v60, v61
	v_max3_f32 v186, v186, v62, v63
	v_max3_f32 v186, v186, v32, v33
	v_max3_f32 v186, v186, v34, v35
	v_max3_f32 v186, v186, v36, v37
	v_max3_f32 v186, v186, v38, v39
	s_waitcnt lgkmcnt(6)
	v_mfma_f32_32x32x16_bf16 v[0:15], v[124:127], v[196:199], v[0:15]
	ds_read_b64_tr_b16 v[196:197], v168 offset:0x1200
	ds_read_b64_tr_b16 v[198:199], v168 offset:0x1a00
	v_max3_f32 v186, v186, v40, v41
	v_max3_f32 v186, v186, v42, v43
	v_max3_f32 v186, v186, v44, v45
	v_max3_f32 v186, v186, v46, v47
	v_mov_b32_e32 v189, v186
	s_nop 1
	v_permlane32_swap_b32_e32 v186, v189
	v_max_f32_e32 v186, v186, v189
	v_sub_f32_e32 v189, v186, v185
	v_max_f32_e32 v186, v185, v186
	v_cmp_ge_f32_e32 vcc, s46, v189
	s_cmp_eq_u64 vcc, exec
	s_waitcnt lgkmcnt(6)
	v_mfma_f32_32x32x16_bf16 v[0:15], v[132:135], v[200:203], v[0:15]
	ds_read_b64_tr_b16 v[200:201], v168 offset:0x2200
	ds_read_b64_tr_b16 v[202:203], v168 offset:0x2a00
	ds_read_b64_tr_b16 v[208:209], v168 offset:0x3200
	ds_read_b64_tr_b16 v[210:211], v168 offset:0x3a00
	s_cselect_b64 s[6:7], -1, 0
	s_cbranch_scc0 .Lmla_rareB
.Lmla_backB:
	v_cndmask_b32_e64 v253, v186, v185, s[6:7]
	v_mul_f32_e32 v250, 0xbe16c740, v253
	s_waitcnt lgkmcnt(8)
	v_mfma_f32_32x32x16_bf16 v[0:15], v[128:131], v[204:207], v[0:15]
	v_fmamk_f32 v48, v48, 0x3e16c740, v250
	v_fmamk_f32 v49, v49, 0x3e16c740, v250
	v_fmamk_f32 v50, v50, 0x3e16c740, v250
	v_fmamk_f32 v51, v51, 0x3e16c740, v250
	v_fmamk_f32 v52, v52, 0x3e16c740, v250
	v_fmamk_f32 v53, v53, 0x3e16c740, v250
	v_fmamk_f32 v54, v54, 0x3e16c740, v250
	v_fmamk_f32 v55, v55, 0x3e16c740, v250
	v_fmamk_f32 v56, v56, 0x3e16c740, v250
	v_fmamk_f32 v57, v57, 0x3e16c740, v250
	v_fmamk_f32 v58, v58, 0x3e16c740, v250
	v_fmamk_f32 v59, v59, 0x3e16c740, v250
	s_waitcnt lgkmcnt(6)
	v_mfma_f32_32x32x16_bf16 v[16:31], v[120:123], v[192:195], v[16:31]
	v_fmamk_f32 v60, v60, 0x3e16c740, v250
	v_fmamk_f32 v61, v61, 0x3e16c740, v250
	v_fmamk_f32 v62, v62, 0x3e16c740, v250
	v_fmamk_f32 v63, v63, 0x3e16c740, v250
	v_exp_f32_e32 v185, v53
	v_exp_f32_e32 v186, v55
	v_exp_f32_e32 v122, v56
	v_exp_f32_e32 v123, v58
	s_waitcnt lgkmcnt(4)
	v_mfma_f32_32x32x16_bf16 v[16:31], v[124:127], v[196:199], v[16:31]
	v_exp_f32_e32 v124, v60
	v_exp_f32_e32 v125, v57
	v_exp_f32_e32 v126, v59
	v_exp_f32_e32 v127, v61
	s_waitcnt lgkmcnt(2)
	v_mfma_f32_32x32x16_bf16 v[16:31], v[132:135], v[200:203], v[16:31]
	v_exp_f32_e32 v132, v52
	v_exp_f32_e32 v133, v54
	v_exp_f32_e32 v134, v49
	v_exp_f32_e32 v135, v51
	s_waitcnt lgkmcnt(0)
	v_mfma_f32_32x32x16_bf16 v[16:31], v[128:131], v[208:211], v[16:31]
	v_exp_f32_e32 v128, v62
	v_exp_f32_e32 v129, v63
	v_exp_f32_e32 v130, v48
	v_exp_f32_e32 v131, v50
	s_barrier
	s_waitcnt vmcnt(4)
	s_cmp_lg_u64 s[10:11], 0
	s_cbranch_scc0 .Lmla_nodrain
	s_waitcnt vmcnt(0)

; __device__ __forceinline__ void partialSM(f32x16& p0, f32x16& p1, float& m_reg, float& mn, float& alpha, float C, float thr) {
;     ...
;   if (__builtin_expect(__all(pmax - m_reg <= thr), 1)) { mn = m_reg; alpha = 1.f; }
;   else { mn = fmaxf(m_reg, pmax); alpha = __builtin_amdgcn_exp2f((m_reg - mn) * C); m_reg = mn; }
.Lmla_rareA:
	v_sub_f32_e32 v252, v120, v121
	v_mul_f32_e32 v252, 0x3e16c740, v252
	v_exp_f32_e32 v252, v252
	s_branch .Lmla_backA
.Lmla_rareB:
	v_sub_f32_e32 v252, v185, v186
	v_mul_f32_e32 v252, 0x3e16c740, v252
	v_exp_f32_e32 v252, v252
	s_branch .Lmla_backB

; #define LAS __attribute__((address_space(3)))
; __device__ __forceinline__ void finishSM(f32x16& p0, f32x16& p1, float alpha, float& l_reg, bf16x8& pa0, bf16x8& pa1, bf16x8& pa2, bf16x8& pa3) {
; #pragma unroll
;   for (int r = 0; r < 16; ++r) p1[r] = __builtin_amdgcn_exp2f(p1[r]);
;   float ps = 0;
; #pragma unroll
;   for (int r = 0; r < 16; ++r) ps += p0[r];
; #pragma unroll
;   for (int r = 0; r < 16; ++r) ps += p1[r];
;   { auto rr = __builtin_amdgcn_permlane32_swap(__float_as_uint(ps), __float_as_uint(ps), false, false);
;     ps = __uint_as_float(rr[0]) + __uint_as_float(rr[1]); }
;   l_reg = l_reg * alpha + ps;
;     ...
;   PK4(p0, 0, pa0); PK4(p0, 8, pa1); PK4(p1, 0, pa2); PK4(p1, 8, pa3);
;     ...
; }
; template <int NDQ>
; __device__ __forceinline__ void qkt(f32x16& p0, f32x16& p1, const LAS char* Ks, const bf16x8* qr, int r32, int hi) {
;   p0 = f32x16{}; p1 = f32x16{};
; #pragma unroll
;   for (int d0 = 0; d0 < NDQ; ++d0) { const int cb = (d0 * 16 + hi * 8) * 2;
;     bf16x8 b0 = *reinterpret_cast<const LAS bf16x8*>(Ks + KSWZ(r32, cb));
;     bf16x8 b1 = *reinterpret_cast<const LAS bf16x8*>(Ks + KSWZ(32 + r32, cb));
;     p0 = __builtin_amdgcn_mfma_f32_32x32x16_bf16(b0, qr[d0], p0, 0, 0, 0);
;     p1 = __builtin_amdgcn_mfma_f32_32x32x16_bf16(b1, qr[d0], p1, 0, 0, 0); }
; }
.LBB0_2123:
	ds_read_b128 v[64:67], v199 offset:49152
	ds_read_b128 v[68:71], v199 offset:57344
	ds_read_b128 v[216:219], v200 offset:49152
	ds_read_b128 v[220:223], v200 offset:57344
	v_add_f32_e32 v161, 0, v236
	v_add_f32_e32 v161, v237, v161
	s_waitcnt lgkmcnt(3)
	v_mfma_f32_32x32x16_bf16 v[80:95], v[64:67], v[124:127], 0
	v_add_f32_e32 v161, v238, v161
	v_add_f32_e32 v161, v239, v161
	v_add_f32_e32 v161, v240, v161
	v_add_f32_e32 v161, v241, v161
	v_add_f32_e32 v161, v242, v161
	v_add_f32_e32 v161, v243, v161
	s_waitcnt lgkmcnt(2)
	v_mfma_f32_32x32x16_bf16 v[64:79], v[68:71], v[124:127], 0
	v_add_f32_e32 v161, v244, v161
	v_add_f32_e32 v161, v245, v161
	v_add_f32_e32 v161, v246, v161
	v_add_f32_e32 v161, v247, v161
	v_exp_f32_e32 v154, v154
	s_waitcnt lgkmcnt(1)
	v_mfma_f32_32x32x16_bf16 v[80:95], v[216:219], v[120:123], v[80:95]
	v_add_f32_e32 v161, v248, v161
	v_exp_f32_e32 v155, v155
	v_add_f32_e32 v161, v249, v161
	v_exp_f32_e32 v152, v152
	s_waitcnt lgkmcnt(0)
	v_mfma_f32_32x32x16_bf16 v[64:79], v[220:223], v[120:123], v[64:79]
	ds_read_b128 v[216:219], v201 offset:49152
	ds_read_b128 v[220:223], v201 offset:57344
	v_add_f32_e32 v161, v250, v161
	v_exp_f32_e32 v153, v153
	v_add_f32_e32 v161, v251, v161
	v_exp_f32_e32 v148, v148
	s_waitcnt lgkmcnt(1)
	v_mfma_f32_32x32x16_bf16 v[80:95], v[216:219], v[116:119], v[80:95]
	v_add_f32_e32 v161, v154, v161
	v_exp_f32_e32 v149, v149
	v_add_f32_e32 v161, v155, v161
	v_exp_f32_e32 v146, v146
	s_waitcnt lgkmcnt(0)
	v_mfma_f32_32x32x16_bf16 v[64:79], v[220:223], v[116:119], v[64:79]
	ds_read_b128 v[216:219], v202 offset:49152
	ds_read_b128 v[220:223], v202 offset:57344
	v_add_f32_e32 v161, v152, v161
	v_exp_f32_e32 v147, v147
	v_add_f32_e32 v161, v153, v161
	v_exp_f32_e32 v144, v144
	s_waitcnt lgkmcnt(1)
	v_mfma_f32_32x32x16_bf16 v[80:95], v[216:219], v[112:115], v[80:95]
	v_add_f32_e32 v161, v148, v161
	v_exp_f32_e32 v145, v145
	v_add_f32_e32 v161, v149, v161
	v_exp_f32_e32 v158, v158
	s_waitcnt lgkmcnt(0)
	v_mfma_f32_32x32x16_bf16 v[64:79], v[220:223], v[112:115], v[64:79]
	ds_read_b128 v[216:219], v203 offset:49152
	ds_read_b128 v[220:223], v203 offset:57344
	v_add_f32_e32 v161, v146, v161
	v_exp_f32_e32 v159, v159
	v_add_f32_e32 v161, v147, v161
	v_exp_f32_e32 v156, v156
	s_waitcnt lgkmcnt(1)
	v_mfma_f32_32x32x16_bf16 v[80:95], v[216:219], v[108:111], v[80:95]
	v_add_f32_e32 v161, v144, v161
	v_exp_f32_e32 v157, v157
	v_add_f32_e32 v161, v145, v161
	v_exp_f32_e32 v150, v150
	s_waitcnt lgkmcnt(0)
	v_mfma_f32_32x32x16_bf16 v[64:79], v[220:223], v[108:111], v[64:79]
	ds_read_b128 v[216:219], v204 offset:49152
	ds_read_b128 v[220:223], v204 offset:57344
	v_add_f32_e32 v161, v158, v161
	v_exp_f32_e32 v151, v151
	v_add_f32_e32 v161, v159, v161
	v_add_f32_e32 v161, v156, v161
	v_add_f32_e32 v161, v157, v161
	s_waitcnt lgkmcnt(1)
	v_mfma_f32_32x32x16_bf16 v[80:95], v[216:219], v[104:107], v[80:95]
	v_add_f32_e32 v161, v150, v161
	v_add_f32_e32 v208, v151, v161
	v_mov_b32_e32 v209, v208
	v_cvt_pk_bf16_f32 v210, v236, v237
	v_cvt_pk_bf16_f32 v211, v238, v239
	v_cvt_pk_bf16_f32 v212, v240, v241
	s_waitcnt lgkmcnt(0)
	v_mfma_f32_32x32x16_bf16 v[64:79], v[220:223], v[104:107], v[64:79]
	ds_read_b128 v[216:219], v205 offset:49152
	ds_read_b128 v[220:223], v205 offset:57344
	v_permlane32_swap_b32_e32 v208, v209
	v_cvt_pk_bf16_f32 v213, v242, v243
	v_cvt_pk_bf16_f32 v170, v244, v245
	v_cvt_pk_bf16_f32 v171, v246, v247
	v_permlane32_swap_b32_e32 v210, v212
	v_cvt_pk_bf16_f32 v172, v248, v249
	s_waitcnt lgkmcnt(1)
	v_mfma_f32_32x32x16_bf16 v[80:95], v[216:219], v[100:103], v[80:95]
	v_cvt_pk_bf16_f32 v173, v250, v251
	v_cvt_pk_bf16_f32 v162, v154, v155
	v_cvt_pk_bf16_f32 v163, v152, v153
	v_cvt_pk_bf16_f32 v164, v148, v149
	v_cvt_pk_bf16_f32 v165, v146, v147
	v_cvt_pk_bf16_f32 v166, v144, v145
	s_waitcnt lgkmcnt(0)
	v_mfma_f32_32x32x16_bf16 v[64:79], v[220:223], v[100:103], v[64:79]
	ds_read_b128 v[216:219], v206 offset:49152
	ds_read_b128 v[220:223], v206 offset:57344
	v_cvt_pk_bf16_f32 v167, v158, v159
	v_cvt_pk_bf16_f32 v168, v156, v157
	v_cvt_pk_bf16_f32 v169, v150, v151
	v_permlane32_swap_b32_e32 v211, v213
	v_permlane32_swap_b32_e32 v170, v172
	v_permlane32_swap_b32_e32 v171, v173
	s_waitcnt lgkmcnt(1)
	v_mfma_f32_32x32x16_bf16 v[80:95], v[216:219], v[96:99], v[80:95]
	v_permlane32_swap_b32_e32 v162, v164
	v_permlane32_swap_b32_e32 v163, v165
	v_permlane32_swap_b32_e32 v166, v168
	v_permlane32_swap_b32_e32 v167, v169
	s_waitcnt lgkmcnt(0)
	v_mfma_f32_32x32x16_bf16 v[64:79], v[220:223], v[96:99], v[64:79]
	v_add_co_u32_e32 v148, vcc, s50, v184
	s_nop 1
	v_addc_co_u32_e32 v149, vcc, -1, v185, vcc
	v_add_co_u32_e32 v152, vcc, s51, v184
	s_nop 1
	v_addc_co_u32_e32 v153, vcc, -1, v185, vcc
	global_load_dwordx4 v[144:147], v[148:149], off
	s_nop 0
	global_load_dwordx4 v[148:151], v[148:149], off offset:-512
	s_nop 0
	global_load_dwordx4 v[156:159], v[152:153], off
	s_nop 0
	global_load_dwordx4 v[152:155], v[152:153], off offset:-512
	s_waitcnt vmcnt(4)
	ds_write_b128 v195, v[140:143] offset:32768
	ds_write_b128 v196, v[132:135] offset:32768
	ds_read_b64_tr_b16 v[214:215], v194 offset:0
	ds_read_b64_tr_b16 v[216:217], v194 offset:0x800
	ds_read_b64_tr_b16 v[218:219], v194 offset:0x1000
	ds_read_b64_tr_b16 v[220:221], v194 offset:0x1800
	ds_read_b64_tr_b16 v[222:223], v194 offset:0x2000
	ds_read_b64_tr_b16 v[224:225], v194 offset:0x2800
	ds_read_b64_tr_b16 v[226:227], v194 offset:0x3000
	ds_read_b64_tr_b16 v[228:229], v194 offset:0x3800
	s_waitcnt lgkmcnt(6)
; #define SBAR() __builtin_amdgcn_sched_barrier(0)
; __device__ __forceinline__ void partialSM(f32x16& p0, f32x16& p1, float& m_reg, float& mn, float& alpha, float C, float thr) {
;   float pmax = p0[0];
; #pragma unroll
;   for (int r = 1; r < 16; ++r) pmax = fmaxf(pmax, p0[r]);
; #pragma unroll
;   for (int r = 0; r < 16; ++r) pmax = fmaxf(pmax, p1[r]);
;   { auto rr = __builtin_amdgcn_permlane32_swap(__float_as_uint(pmax), __float_as_uint(pmax), false, false);
;     pmax = fmaxf(__uint_as_float(rr[0]), __uint_as_float(rr[1])); }
;   if (__builtin_expect(__all(pmax - m_reg <= thr), 1)) { mn = m_reg; alpha = 1.f; }
;   else { mn = fmaxf(m_reg, pmax); alpha = __builtin_amdgcn_exp2f((m_reg - mn) * C); m_reg = mn; }
;   const float mnC = -mn * C;
; #pragma unroll
;   for (int r = 0; r < 16; ++r) p0[r] = fmaf(p0[r], C, mnC);
; #pragma unroll
;   for (int r = 0; r < 16; ++r) p1[r] = fmaf(p1[r], C, mnC);
; #pragma unroll
;   for (int r = 0; r < 16; ++r) p0[r] = __builtin_amdgcn_exp2f(p0[r]);
; }
; template <int D0> __device__ __forceinline__ void pv_one(f32x16& od, int vb, bf16x8 pa0, bf16x8 pa1, bf16x8 pa2, bf16x8 pa3) {
;   const s16x4 l0 = tr_read<v_rd_off(D0, 0, 0)>(vb), h0 = tr_read<v_rd_off(D0, 0, 1)>(vb), l1 = tr_read<v_rd_off(D0, 1, 0)>(vb), h1 = tr_read<v_rd_off(D0, 1, 1)>(vb);
;   const s16x4 l2 = tr_read<v_rd_off(D0, 2, 0)>(vb), h2 = tr_read<v_rd_off(D0, 2, 1)>(vb), l3 = tr_read<v_rd_off(D0, 3, 0)>(vb), h3 = tr_read<v_rd_off(D0, 3, 1)>(vb);
;   asm volatile("s_waitcnt lgkmcnt(0)" ::: "memory"); SBAR();
;     ...
;   od = __builtin_amdgcn_mfma_f32_32x32x16_bf16(pa0, PK(l0, h0), od, 0, 0, 0);
;   od = __builtin_amdgcn_mfma_f32_32x32x16_bf16(pa1, PK(l1, h1), od, 0, 0, 0);
;   od = __builtin_amdgcn_mfma_f32_32x32x16_bf16(pa2, PK(l2, h2), od, 0, 0, 0);
;   od = __builtin_amdgcn_mfma_f32_32x32x16_bf16(pa3, PK(l3, h3), od, 0, 0, 0);
;     ...
; }
; template <int NDV>
; __device__ __forceinline__ void pv_d0(f32x16* o, int vb, bf16x8 pa0, bf16x8 pa1, bf16x8 pa2, bf16x8 pa3) {
;   pv_one<0>(o[0], vb, pa0, pa1, pa2, pa3); pv_one<1>(o[1], vb, pa0, pa1, pa2, pa3);
;   if constexpr (NDV == 4) { pv_one<2>(o[2], vb, pa0, pa1, pa2, pa3); pv_one<3>(o[3], vb, pa0, pa1, pa2, pa3); }
; }
	v_mfma_f32_32x32x16_bf16 v[0:15], v[210:213], v[214:217], v[0:15]
	ds_read_b64_tr_b16 v[214:215], v194 offset:0x200
	ds_read_b64_tr_b16 v[216:217], v194 offset:0xa00
	v_max_f32_e32 v161, v80, v81
	v_max3_f32 v161, v161, v82, v83
	v_max3_f32 v161, v161, v84, v85
	v_max3_f32 v161, v161, v86, v87
	v_max3_f32 v161, v161, v88, v89
	v_max3_f32 v161, v161, v90, v91
	s_waitcnt lgkmcnt(6)
	v_mfma_f32_32x32x16_bf16 v[0:15], v[170:173], v[218:221], v[0:15]
	ds_read_b64_tr_b16 v[218:219], v194 offset:0x1200
	ds_read_b64_tr_b16 v[220:221], v194 offset:0x1a00
	v_max3_f32 v161, v161, v92, v93
	v_max3_f32 v161, v161, v94, v95
	v_max3_f32 v161, v161, v64, v65
	v_max3_f32 v161, v161, v66, v67
	v_max3_f32 v161, v161, v68, v69
	v_max3_f32 v161, v161, v70, v71
	s_waitcnt lgkmcnt(6)
	v_mfma_f32_32x32x16_bf16 v[0:15], v[162:165], v[222:225], v[0:15]
	ds_read_b64_tr_b16 v[222:223], v194 offset:0x2200
	ds_read_b64_tr_b16 v[224:225], v194 offset:0x2a00
	ds_read_b64_tr_b16 v[230:231], v194 offset:0x3200
	ds_read_b64_tr_b16 v[232:233], v194 offset:0x3a00
	v_max3_f32 v161, v161, v72, v73
	v_max3_f32 v161, v161, v74, v75
	v_max3_f32 v161, v161, v76, v77
	v_max3_f32 v161, v161, v78, v79
	v_mov_b32_e32 v174, v161
	s_nop 1
	s_waitcnt lgkmcnt(8)
	v_mfma_f32_32x32x16_bf16 v[0:15], v[166:169], v[226:229], v[0:15]
	v_permlane32_swap_b32_e32 v161, v174
	v_max_f32_e32 v161, v161, v174
	v_sub_f32_e32 v175, v161, v160
	v_max_f32_e32 v161, v160, v161
	v_cmp_ge_f32_e32 vcc, s48, v175
	s_cmp_eq_u64 vcc, exec
	s_waitcnt lgkmcnt(6)
	v_mfma_f32_32x32x16_bf16 v[48:63], v[210:213], v[214:217], v[48:63]
	ds_read_b64_tr_b16 v[214:215], v194 offset:0x400
	ds_read_b64_tr_b16 v[216:217], v194 offset:0xc00
	s_cselect_b64 s[2:3], -1, 0
	s_cbranch_scc0 .Lgqa_rareA
.Lgqa_backA:
	v_cndmask_b32_e64 v234, v161, v160, s[2:3]
	v_mul_f32_e32 v175, 0xbe0293ee, v234
	v_fmamk_f32 v80, v80, 0x3e0293ee, v175
	s_waitcnt lgkmcnt(6)
	v_mfma_f32_32x32x16_bf16 v[48:63], v[170:173], v[218:221], v[48:63]
	ds_read_b64_tr_b16 v[218:219], v194 offset:0x1400
	ds_read_b64_tr_b16 v[220:221], v194 offset:0x1c00
	v_fmamk_f32 v81, v81, 0x3e0293ee, v175
	v_fmamk_f32 v82, v82, 0x3e0293ee, v175
	v_fmamk_f32 v83, v83, 0x3e0293ee, v175
	v_fmamk_f32 v84, v84, 0x3e0293ee, v175
	v_fmamk_f32 v85, v85, 0x3e0293ee, v175
	v_fmamk_f32 v86, v86, 0x3e0293ee, v175
	s_waitcnt lgkmcnt(6)
	v_mfma_f32_32x32x16_bf16 v[48:63], v[162:165], v[222:225], v[48:63]
	ds_read_b64_tr_b16 v[222:223], v194 offset:0x2400
	ds_read_b64_tr_b16 v[224:225], v194 offset:0x2c00
	ds_read_b64_tr_b16 v[226:227], v194 offset:0x3400
	ds_read_b64_tr_b16 v[228:229], v194 offset:0x3c00
	v_fmamk_f32 v87, v87, 0x3e0293ee, v175
	v_fmamk_f32 v88, v88, 0x3e0293ee, v175
	v_fmamk_f32 v89, v89, 0x3e0293ee, v175
	v_fmamk_f32 v90, v90, 0x3e0293ee, v175
	v_fmamk_f32 v91, v91, 0x3e0293ee, v175
	v_fmamk_f32 v92, v92, 0x3e0293ee, v175
	s_waitcnt lgkmcnt(8)
	v_mfma_f32_32x32x16_bf16 v[48:63], v[166:169], v[230:233], v[48:63]
	v_fmamk_f32 v93, v93, 0x3e0293ee, v175
	v_fmamk_f32 v94, v94, 0x3e0293ee, v175
	v_fmamk_f32 v95, v95, 0x3e0293ee, v175
	v_exp_f32_e32 v236, v80
	s_waitcnt lgkmcnt(6)
	v_mfma_f32_32x32x16_bf16 v[32:47], v[210:213], v[214:217], v[32:47]
	ds_read_b64_tr_b16 v[214:215], v194 offset:0x600
	ds_read_b64_tr_b16 v[216:217], v194 offset:0xe00
	v_exp_f32_e32 v237, v81
	v_exp_f32_e32 v238, v82
	v_exp_f32_e32 v239, v83
	s_waitcnt lgkmcnt(6)
	v_mfma_f32_32x32x16_bf16 v[32:47], v[170:173], v[218:221], v[32:47]
	ds_read_b64_tr_b16 v[218:219], v194 offset:0x1600
	ds_read_b64_tr_b16 v[220:221], v194 offset:0x1e00
	v_exp_f32_e32 v240, v84
	v_exp_f32_e32 v241, v85
	v_exp_f32_e32 v242, v86
	s_waitcnt lgkmcnt(6)
	v_mfma_f32_32x32x16_bf16 v[32:47], v[162:165], v[222:225], v[32:47]
	ds_read_b64_tr_b16 v[222:223], v194 offset:0x2600
	ds_read_b64_tr_b16 v[224:225], v194 offset:0x2e00
	ds_read_b64_tr_b16 v[230:231], v194 offset:0x3600
	ds_read_b64_tr_b16 v[232:233], v194 offset:0x3e00
	v_exp_f32_e32 v243, v87
	v_exp_f32_e32 v244, v88
	v_exp_f32_e32 v245, v89
	s_waitcnt lgkmcnt(8)
	v_mfma_f32_32x32x16_bf16 v[32:47], v[166:169], v[226:229], v[32:47]
	v_exp_f32_e32 v246, v90
	v_exp_f32_e32 v247, v91
	v_exp_f32_e32 v248, v92
	s_waitcnt lgkmcnt(6)
	v_mfma_f32_32x32x16_bf16 v[16:31], v[210:213], v[214:217], v[16:31]
	v_exp_f32_e32 v249, v93
	v_exp_f32_e32 v250, v94
	v_exp_f32_e32 v251, v95
	s_waitcnt lgkmcnt(4)
	v_mfma_f32_32x32x16_bf16 v[16:31], v[170:173], v[218:221], v[16:31]
	s_waitcnt lgkmcnt(2)
	v_mfma_f32_32x32x16_bf16 v[16:31], v[162:165], v[222:225], v[16:31]
	s_waitcnt lgkmcnt(0)
	v_mfma_f32_32x32x16_bf16 v[16:31], v[166:169], v[230:233], v[16:31]
	s_barrier
	s_waitcnt vmcnt(4)
	v_cndmask_b32_e64 v210, v235, 1.0, s[2:3]
	v_cmp_gt_f32_e32 vcc, 1.0, v210
	s_waitcnt vmcnt(4)
	ds_write_b128 v197, v[128:131]
	ds_write_b128 v198, v[136:139]
	s_cbranch_vccz .LBB0_2127
	s_and_saveexec_b64 s[30:31], s[0:1]
	ds_write_b32 v191, v210 offset:128
	s_or_b64 exec, exec, s[30:31]
	s_waitcnt lgkmcnt(0)
	v_add_u32_e32 v174, v183, v176
	ds_read_b128 v[162:165], v174 offset:224
	ds_read_b128 v[166:169], v174 offset:192
	ds_read_b128 v[170:173], v174 offset:160
	ds_read_b128 v[212:215], v174 offset:128
	s_waitcnt lgkmcnt(3)
	v_pk_mul_f32 v[12:13], v[12:13], v[162:163]
	s_waitcnt lgkmcnt(2)
	v_pk_mul_f32 v[8:9], v[8:9], v[166:167]
	s_waitcnt lgkmcnt(1)
	v_pk_mul_f32 v[4:5], v[4:5], v[170:171]
	v_pk_mul_f32 v[14:15], v[14:15], v[164:165]
	v_pk_mul_f32 v[10:11], v[10:11], v[168:169]
	v_pk_mul_f32 v[6:7], v[6:7], v[172:173]
	s_waitcnt lgkmcnt(0)
	v_pk_mul_f32 v[2:3], v[2:3], v[214:215]
	v_pk_mul_f32 v[0:1], v[0:1], v[212:213]
	v_pk_mul_f32 v[60:61], v[60:61], v[162:163]
	v_pk_mul_f32 v[56:57], v[56:57], v[166:167]
	v_pk_mul_f32 v[52:53], v[52:53], v[170:171]
	v_pk_mul_f32 v[62:63], v[62:63], v[164:165]
	v_pk_mul_f32 v[58:59], v[58:59], v[168:169]
	v_pk_mul_f32 v[54:55], v[54:55], v[172:173]
	v_pk_mul_f32 v[50:51], v[50:51], v[214:215]
	v_pk_mul_f32 v[48:49], v[48:49], v[212:213]
	v_pk_mul_f32 v[44:45], v[44:45], v[162:163]
	v_pk_mul_f32 v[40:41], v[40:41], v[166:167]
	v_pk_mul_f32 v[36:37], v[36:37], v[170:171]
	v_pk_mul_f32 v[46:47], v[46:47], v[164:165]
	v_pk_mul_f32 v[42:43], v[42:43], v[168:169]
	v_pk_mul_f32 v[38:39], v[38:39], v[172:173]
	v_pk_mul_f32 v[34:35], v[34:35], v[214:215]
	v_pk_mul_f32 v[32:33], v[32:33], v[212:213]
	v_pk_mul_f32 v[28:29], v[28:29], v[162:163]
	v_pk_mul_f32 v[24:25], v[24:25], v[166:167]
	v_pk_mul_f32 v[20:21], v[20:21], v[170:171]
	v_pk_mul_f32 v[30:31], v[30:31], v[164:165]
	v_pk_mul_f32 v[26:27], v[26:27], v[168:169]
	v_pk_mul_f32 v[22:23], v[22:23], v[172:173]
	v_pk_mul_f32 v[18:19], v[18:19], v[214:215]
	v_pk_mul_f32 v[16:17], v[16:17], v[212:213]

; #define SBAR() __builtin_amdgcn_sched_barrier(0)
; __device__ __forceinline__ void partialSM(f32x16& p0, f32x16& p1, float& m_reg, float& mn, float& alpha, float C, float thr) {
;   float pmax = p0[0];
; #pragma unroll
;   for (int r = 1; r < 16; ++r) pmax = fmaxf(pmax, p0[r]);
; #pragma unroll
;   for (int r = 0; r < 16; ++r) pmax = fmaxf(pmax, p1[r]);
;   { auto rr = __builtin_amdgcn_permlane32_swap(__float_as_uint(pmax), __float_as_uint(pmax), false, false);
;     pmax = fmaxf(__uint_as_float(rr[0]), __uint_as_float(rr[1])); }
;   if (__builtin_expect(__all(pmax - m_reg <= thr), 1)) { mn = m_reg; alpha = 1.f; }
;   else { mn = fmaxf(m_reg, pmax); alpha = __builtin_amdgcn_exp2f((m_reg - mn) * C); m_reg = mn; }
;   const float mnC = -mn * C;
; #pragma unroll
;   for (int r = 0; r < 16; ++r) p0[r] = fmaf(p0[r], C, mnC);
; #pragma unroll
;   for (int r = 0; r < 16; ++r) p1[r] = fmaf(p1[r], C, mnC);
; #pragma unroll
;   for (int r = 0; r < 16; ++r) p0[r] = __builtin_amdgcn_exp2f(p0[r]);
; }
; template <int D0> __device__ __forceinline__ void pv_one(f32x16& od, int vb, bf16x8 pa0, bf16x8 pa1, bf16x8 pa2, bf16x8 pa3) {
;   const s16x4 l0 = tr_read<v_rd_off(D0, 0, 0)>(vb), h0 = tr_read<v_rd_off(D0, 0, 1)>(vb), l1 = tr_read<v_rd_off(D0, 1, 0)>(vb), h1 = tr_read<v_rd_off(D0, 1, 1)>(vb);
;   const s16x4 l2 = tr_read<v_rd_off(D0, 2, 0)>(vb), h2 = tr_read<v_rd_off(D0, 2, 1)>(vb), l3 = tr_read<v_rd_off(D0, 3, 0)>(vb), h3 = tr_read<v_rd_off(D0, 3, 1)>(vb);
;   asm volatile("s_waitcnt lgkmcnt(0)" ::: "memory"); SBAR();
;     ...
;   od = __builtin_amdgcn_mfma_f32_32x32x16_bf16(pa0, PK(l0, h0), od, 0, 0, 0);
;   od = __builtin_amdgcn_mfma_f32_32x32x16_bf16(pa1, PK(l1, h1), od, 0, 0, 0);
;   od = __builtin_amdgcn_mfma_f32_32x32x16_bf16(pa2, PK(l2, h2), od, 0, 0, 0);
;   od = __builtin_amdgcn_mfma_f32_32x32x16_bf16(pa3, PK(l3, h3), od, 0, 0, 0);
;     ...
; }
; template <int NDV>
; __device__ __forceinline__ void pv_d0(f32x16* o, int vb, bf16x8 pa0, bf16x8 pa1, bf16x8 pa2, bf16x8 pa3) {
;   pv_one<0>(o[0], vb, pa0, pa1, pa2, pa3); pv_one<1>(o[1], vb, pa0, pa1, pa2, pa3);
;   if constexpr (NDV == 4) { pv_one<2>(o[2], vb, pa0, pa1, pa2, pa3); pv_one<3>(o[3], vb, pa0, pa1, pa2, pa3); }
; }
.Lgqa_nodrain2:
	ds_write_b128 v195, v[148:151] offset:49152
	ds_write_b128 v196, v[152:155] offset:49152
	ds_read_b64_tr_b16 v[214:215], v193 offset:0
	ds_read_b64_tr_b16 v[216:217], v193 offset:0x800
	ds_read_b64_tr_b16 v[218:219], v193 offset:0x1000
	ds_read_b64_tr_b16 v[220:221], v193 offset:0x1800
	ds_read_b64_tr_b16 v[222:223], v193 offset:0x2000
	ds_read_b64_tr_b16 v[224:225], v193 offset:0x2800
	ds_read_b64_tr_b16 v[226:227], v193 offset:0x3000
	ds_read_b64_tr_b16 v[228:229], v193 offset:0x3800
	s_waitcnt lgkmcnt(6)
	v_mfma_f32_32x32x16_bf16 v[0:15], v[160:163], v[214:217], v[0:15]
	ds_read_b64_tr_b16 v[214:215], v193 offset:0x200
	ds_read_b64_tr_b16 v[216:217], v193 offset:0xa00
	v_max_f32_e32 v234, v80, v81
	v_max3_f32 v234, v234, v82, v83
	v_max3_f32 v234, v234, v84, v85
	v_max3_f32 v234, v234, v86, v87
	v_max3_f32 v234, v234, v88, v89
	v_max3_f32 v234, v234, v90, v91
	s_waitcnt lgkmcnt(6)
	v_mfma_f32_32x32x16_bf16 v[0:15], v[164:167], v[218:221], v[0:15]
	ds_read_b64_tr_b16 v[218:219], v193 offset:0x1200
	ds_read_b64_tr_b16 v[220:221], v193 offset:0x1a00
	v_max3_f32 v234, v234, v92, v93
	v_max3_f32 v234, v234, v94, v95
	v_max3_f32 v234, v234, v64, v65
	v_max3_f32 v234, v234, v66, v67
	v_max3_f32 v234, v234, v68, v69
	v_max3_f32 v234, v234, v70, v71
	s_waitcnt lgkmcnt(6)
	v_mfma_f32_32x32x16_bf16 v[0:15], v[168:171], v[222:225], v[0:15]
	ds_read_b64_tr_b16 v[222:223], v193 offset:0x2200
	ds_read_b64_tr_b16 v[224:225], v193 offset:0x2a00
	ds_read_b64_tr_b16 v[230:231], v193 offset:0x3200
	ds_read_b64_tr_b16 v[232:233], v193 offset:0x3a00
	v_max3_f32 v234, v234, v72, v73
	v_max3_f32 v234, v234, v74, v75
	v_max3_f32 v234, v234, v76, v77
	v_max3_f32 v234, v234, v78, v79
	v_mov_b32_e32 v235, v234
	s_nop 1
	s_waitcnt lgkmcnt(8)
	v_mfma_f32_32x32x16_bf16 v[0:15], v[172:175], v[226:229], v[0:15]
	v_permlane32_swap_b32_e32 v234, v235
	v_max_f32_e32 v234, v234, v235
	v_sub_f32_e32 v235, v234, v211
	v_max_f32_e32 v234, v211, v234
	v_cmp_ge_f32_e32 vcc, s48, v235
	s_cmp_eq_u64 vcc, exec
	s_waitcnt lgkmcnt(6)
	v_mfma_f32_32x32x16_bf16 v[48:63], v[160:163], v[214:217], v[48:63]
	ds_read_b64_tr_b16 v[214:215], v193 offset:0x400
	ds_read_b64_tr_b16 v[216:217], v193 offset:0xc00
	s_cselect_b64 s[2:3], -1, 0
	s_cbranch_scc0 .Lgqa_rareB
.Lgqa_backB:
	v_cndmask_b32_e64 v234, v234, v211, s[2:3]
	v_mul_f32_e32 v252, 0xbe0293ee, v234
	v_fmamk_f32 v80, v80, 0x3e0293ee, v252
	s_waitcnt lgkmcnt(6)
	v_mfma_f32_32x32x16_bf16 v[48:63], v[164:167], v[218:221], v[48:63]
	ds_read_b64_tr_b16 v[218:219], v193 offset:0x1400
	ds_read_b64_tr_b16 v[220:221], v193 offset:0x1c00
	v_fmamk_f32 v81, v81, 0x3e0293ee, v252
	v_fmamk_f32 v82, v82, 0x3e0293ee, v252
	v_fmamk_f32 v83, v83, 0x3e0293ee, v252
	v_fmamk_f32 v84, v84, 0x3e0293ee, v252
	v_fmamk_f32 v85, v85, 0x3e0293ee, v252
	v_fmamk_f32 v86, v86, 0x3e0293ee, v252
	s_waitcnt lgkmcnt(6)
	v_mfma_f32_32x32x16_bf16 v[48:63], v[168:171], v[222:225], v[48:63]
	ds_read_b64_tr_b16 v[222:223], v193 offset:0x2400
	ds_read_b64_tr_b16 v[224:225], v193 offset:0x2c00
	ds_read_b64_tr_b16 v[226:227], v193 offset:0x3400
	ds_read_b64_tr_b16 v[228:229], v193 offset:0x3c00
	v_fmamk_f32 v87, v87, 0x3e0293ee, v252
	v_fmamk_f32 v88, v88, 0x3e0293ee, v252
	v_fmamk_f32 v89, v89, 0x3e0293ee, v252
	v_fmamk_f32 v90, v90, 0x3e0293ee, v252
	v_fmamk_f32 v91, v91, 0x3e0293ee, v252
	v_fmamk_f32 v92, v92, 0x3e0293ee, v252
	s_waitcnt lgkmcnt(8)
	v_mfma_f32_32x32x16_bf16 v[48:63], v[172:175], v[230:233], v[48:63]
	v_fmamk_f32 v93, v93, 0x3e0293ee, v252
	v_fmamk_f32 v94, v94, 0x3e0293ee, v252
	v_fmamk_f32 v95, v95, 0x3e0293ee, v252
	v_exp_f32_e32 v236, v80
	s_waitcnt lgkmcnt(6)
	v_mfma_f32_32x32x16_bf16 v[32:47], v[160:163], v[214:217], v[32:47]
	ds_read_b64_tr_b16 v[214:215], v193 offset:0x600
	ds_read_b64_tr_b16 v[216:217], v193 offset:0xe00
	v_exp_f32_e32 v237, v81
	v_exp_f32_e32 v238, v82
	v_exp_f32_e32 v239, v83
	s_waitcnt lgkmcnt(6)
	v_mfma_f32_32x32x16_bf16 v[32:47], v[164:167], v[218:221], v[32:47]
	ds_read_b64_tr_b16 v[218:219], v193 offset:0x1600
	ds_read_b64_tr_b16 v[220:221], v193 offset:0x1e00
	v_exp_f32_e32 v240, v84
	v_exp_f32_e32 v241, v85
	v_exp_f32_e32 v242, v86
	s_waitcnt lgkmcnt(6)
	v_mfma_f32_32x32x16_bf16 v[32:47], v[168:171], v[222:225], v[32:47]
	ds_read_b64_tr_b16 v[222:223], v193 offset:0x2600
	ds_read_b64_tr_b16 v[224:225], v193 offset:0x2e00
	ds_read_b64_tr_b16 v[230:231], v193 offset:0x3600
	ds_read_b64_tr_b16 v[232:233], v193 offset:0x3e00
	v_exp_f32_e32 v243, v87
	v_exp_f32_e32 v244, v88
	v_exp_f32_e32 v245, v89
	s_waitcnt lgkmcnt(8)
	v_mfma_f32_32x32x16_bf16 v[32:47], v[172:175], v[226:229], v[32:47]
	v_exp_f32_e32 v246, v90
	v_exp_f32_e32 v247, v91
	v_exp_f32_e32 v248, v92
	s_waitcnt lgkmcnt(6)
	v_mfma_f32_32x32x16_bf16 v[16:31], v[160:163], v[214:217], v[16:31]
	v_exp_f32_e32 v249, v93
	v_exp_f32_e32 v250, v94
	v_exp_f32_e32 v251, v95
	s_waitcnt lgkmcnt(4)
	v_mfma_f32_32x32x16_bf16 v[16:31], v[164:167], v[218:221], v[16:31]
	s_waitcnt lgkmcnt(2)
	v_mfma_f32_32x32x16_bf16 v[16:31], v[168:171], v[222:225], v[16:31]
	s_waitcnt lgkmcnt(0)
	v_mfma_f32_32x32x16_bf16 v[16:31], v[172:175], v[230:233], v[16:31]
	s_barrier
	s_waitcnt vmcnt(4)
	s_cmp_lg_u64 s[30:31], 0
	s_cbranch_scc0 .Lgqa_nodrain
	s_waitcnt vmcnt(0)

; __device__ __forceinline__ void partialSM(f32x16& p0, f32x16& p1, float& m_reg, float& mn, float& alpha, float C, float thr) {
;     ...
;   if (__builtin_expect(__all(pmax - m_reg <= thr), 1)) { mn = m_reg; alpha = 1.f; }
;   else { mn = fmaxf(m_reg, pmax); alpha = __builtin_amdgcn_exp2f((m_reg - mn) * C); m_reg = mn; }
.Lgqa_rareA:
	v_sub_f32_e32 v235, v160, v161
	v_mul_f32_e32 v235, 0x3e0293ee, v235
	v_exp_f32_e32 v235, v235
	s_branch .Lgqa_backA
.Lgqa_rareB:
	v_sub_f32_e32 v253, v211, v234
	v_mul_f32_e32 v253, 0x3e0293ee, v253
	v_exp_f32_e32 v253, v253
	s_branch .Lgqa_backB
